# v42 + mLSTM decay-mask build: bcum row values read once (ds_read_b128 + pair) instead of 8 serial LDS round trips in masked blocks
# speedup vs baseline: 1.0221x; 1.0003x over previous
; #define LAS __attribute__((address_space(3)))
; __device__ __forceinline__ void mlstm_item(const P& p, const Ctx& c, int seg, int w, bool save) {
;     ...
;               const u32x4 q0 = *(const LAS u32x4*)(Qs + t * 136 + part * 16), q1 = *(const LAS u32x4*)(Qs + t * 136 + part * 16 + 8);
;               const LAS float* np = nold + d0 + part * 16; const f32x4 n0 = *(const LAS f32x4*)np, n1 = *(const LAS f32x4*)(np + 4), n2 = *(const LAS f32x4*)(np + 8), n3 = *(const LAS f32x4*)(np + 12);
;               qnacc += bflo(q0.x) * n0[0] + bfhi(q0.x) * n0[1] + bflo(q0.y) * n0[2] + bfhi(q0.y) * n0[3] + bflo(q0.z) * n1[0] + bfhi(q0.z) * n1[1] + bflo(q0.w) * n1[2] + bfhi(q0.w) * n1[3]
;                      + bflo(q1.x) * n2[0] + bfhi(q1.x) * n2[1] + bflo(q1.y) * n2[2] + bfhi(q1.y) * n2[3] + bflo(q1.z) * n3[0] + bfhi(q1.z) * n3[1] + bflo(q1.w) * n3[2] + bfhi(q1.w) * n3[3]; }
;             { const int dd = tidv >> 2, part = tidv & 3;
;               const u32x4 k0 = *(const LAS u32x4*)(KTs + dd * 72 + part * 16), k1 = *(const LAS u32x4*)(KTs + dd * 72 + part * 16 + 8);
;               const LAS float* wp = wgt + part * 16; const f32x4 w0 = *(const LAS f32x4*)wp, w1 = *(const LAS f32x4*)(wp + 4), w2 = *(const LAS f32x4*)(wp + 8), w3 = *(const LAS f32x4*)(wp + 12);
;               float a = bflo(k0.x) * w0[0] + bfhi(k0.x) * w0[1] + bflo(k0.y) * w0[2] + bfhi(k0.y) * w0[3] + bflo(k0.z) * w1[0] + bfhi(k0.z) * w1[1] + bflo(k0.w) * w1[2] + bfhi(k0.w) * w1[3]
;                       + bflo(k1.x) * w2[0] + bfhi(k1.x) * w2[1] + bflo(k1.y) * w2[2] + bfhi(k1.y) * w2[3] + bflo(k1.z) * w3[0] + bfhi(k1.z) * w3[1] + bflo(k1.w) * w3[2] + bfhi(k1.w) * w3[3];
;               a = dpp_add<0xB1>(a); a = dpp_add<0x4E>(a);
;               if (part == 0) nnew[d0 + dd] = gtot * nold[d0 + dd] + a; }
;         }
;         qnacc = dpp_add<0xB1>(qnacc); qnacc = dpp_add<0x4E>(qnacc); qnacc = dpp_add<0x141>(qnacc);
;         if ((tidv & 7) == 0) qn[tidv >> 3] = qnacc;
; #pragma unroll
;         for (int x = 0; x < 2; ++x) { const int ti = c.wv * 2 + x, tm = ti >> 2, tn = ti & 3; const int s = tn * 16 + l15; const float bs = bcum[s] - ipr[s];
; #pragma unroll
;             for (int jj = 0; jj < 4; ++jj) { const int t = tm * 16 + quad * 4 + jj; const float v = (s <= t) ? Sa[x][jj] * __expf(bcum[t] - bs) : 0.f; Sp[t * 72 + s] = f2bf(v); } }
.LBB0_381:
	s_or_b64 exec, exec, s[16:17]
	v_lshlrev_b32_e32 v4, 16, v94
	v_and_b32_e32 v94, 0xffff0000, v94
	v_mul_f32_e32 v94, v103, v94
	v_fmac_f32_e32 v94, v102, v4
	v_lshlrev_b32_e32 v4, 16, v95
	v_fmac_f32_e32 v94, v104, v4
	v_and_b32_e32 v4, 0xffff0000, v95
	v_fmac_f32_e32 v94, v105, v4
	v_lshlrev_b32_e32 v4, 16, v96
	v_fmac_f32_e32 v94, v98, v4
	v_and_b32_e32 v4, 0xffff0000, v96
	v_fmac_f32_e32 v94, v99, v4
	v_lshlrev_b32_e32 v4, 16, v97
	v_fmac_f32_e32 v94, v100, v4
	v_and_b32_e32 v4, 0xffff0000, v97
	v_fmac_f32_e32 v94, v101, v4
	v_lshlrev_b32_e32 v4, 16, v82
	v_fmac_f32_e32 v94, v90, v4
	v_and_b32_e32 v4, 0xffff0000, v82
	v_fmac_f32_e32 v94, v91, v4
	v_lshlrev_b32_e32 v4, 16, v83
	v_fmac_f32_e32 v94, v92, v4
	v_and_b32_e32 v4, 0xffff0000, v83
	v_and_b32_e32 v83, 0xffff0000, v118
	v_lshlrev_b32_e32 v82, 16, v118
	v_mul_f32_e32 v83, v127, v83
	v_fmac_f32_e32 v83, v126, v82
	v_lshlrev_b32_e32 v82, 16, v119
	v_fmac_f32_e32 v83, v128, v82
	v_and_b32_e32 v82, 0xffff0000, v119
	v_fmac_f32_e32 v83, v129, v82
	v_lshlrev_b32_e32 v82, 16, v120
	v_fmac_f32_e32 v83, v122, v82
	v_and_b32_e32 v82, 0xffff0000, v120
	v_fmac_f32_e32 v83, v123, v82
	v_lshlrev_b32_e32 v82, 16, v121
	v_fmac_f32_e32 v83, v124, v82
	v_and_b32_e32 v82, 0xffff0000, v121
	v_fmac_f32_e32 v83, v125, v82
	v_lshlrev_b32_e32 v82, 16, v106
	v_fmac_f32_e32 v83, v114, v82
	v_and_b32_e32 v82, 0xffff0000, v106
	v_fmac_f32_e32 v83, v115, v82
	v_lshlrev_b32_e32 v82, 16, v107
	v_fmac_f32_e32 v94, v93, v4
	v_lshlrev_b32_e32 v4, 16, v84
	v_fmac_f32_e32 v83, v116, v82
	v_and_b32_e32 v82, 0xffff0000, v107
	v_fmac_f32_e32 v94, v86, v4
	v_and_b32_e32 v4, 0xffff0000, v84
	v_fmac_f32_e32 v83, v117, v82
	v_lshlrev_b32_e32 v82, 16, v108
	v_fmac_f32_e32 v94, v87, v4
	v_lshlrev_b32_e32 v4, 16, v85
	v_fmac_f32_e32 v83, v110, v82
	v_and_b32_e32 v82, 0xffff0000, v108
	v_fmac_f32_e32 v94, v88, v4
	v_and_b32_e32 v4, 0xffff0000, v85
	v_fmac_f32_e32 v83, v111, v82
	v_lshlrev_b32_e32 v82, 16, v109
	v_fmac_f32_e32 v94, v89, v4
	v_fmac_f32_e32 v83, v112, v82
	v_and_b32_e32 v82, 0xffff0000, v109
	v_add_f32_e32 v4, 0, v94
	v_fmac_f32_e32 v83, v113, v82
	v_add_f32_e32 v4, v4, v83
	v_and_b32_e32 v83, 0xffff0000, v154
	v_lshlrev_b32_e32 v82, 16, v154
	v_mul_f32_e32 v83, v167, v83
	v_fmac_f32_e32 v83, v166, v82
	v_lshlrev_b32_e32 v82, 16, v155
	v_fmac_f32_e32 v83, v168, v82
	v_and_b32_e32 v82, 0xffff0000, v155
	v_fmac_f32_e32 v83, v169, v82
	v_lshlrev_b32_e32 v82, 16, v156
	v_fmac_f32_e32 v83, v162, v82
	v_and_b32_e32 v82, 0xffff0000, v156
	v_fmac_f32_e32 v83, v163, v82
	v_lshlrev_b32_e32 v82, 16, v157
	v_fmac_f32_e32 v83, v164, v82
	v_and_b32_e32 v82, 0xffff0000, v157
	v_fmac_f32_e32 v83, v165, v82
	v_lshlrev_b32_e32 v82, 16, v146
	v_fmac_f32_e32 v83, v158, v82
	v_and_b32_e32 v82, 0xffff0000, v146
	v_fmac_f32_e32 v83, v159, v82
	v_lshlrev_b32_e32 v82, 16, v147
	v_fmac_f32_e32 v83, v160, v82
	v_and_b32_e32 v82, 0xffff0000, v147
	v_fmac_f32_e32 v83, v161, v82
	v_lshlrev_b32_e32 v82, 16, v148
	v_fmac_f32_e32 v83, v150, v82
	v_and_b32_e32 v82, 0xffff0000, v148
	v_fmac_f32_e32 v83, v151, v82
	v_lshlrev_b32_e32 v82, 16, v149
	v_fmac_f32_e32 v83, v152, v82
	v_and_b32_e32 v82, 0xffff0000, v149
	v_fmac_f32_e32 v83, v153, v82
	v_add_f32_e32 v4, v4, v83
	v_and_b32_e32 v83, 7, v191
	v_cmp_eq_u32_e32 vcc, 0, v83
	v_add_f32_dpp v4, v4, v4 quad_perm:[1,0,3,2] row_mask:0xf bank_mask:0xf bound_ctrl:1
	s_nop 1
	v_add_f32_dpp v4, v4, v4 quad_perm:[2,3,0,1] row_mask:0xf bank_mask:0xf bound_ctrl:1
	s_nop 1
	v_mov_b32_dpp v82, v4 row_half_mirror row_mask:0xf bank_mask:0xf bound_ctrl:1
	s_and_saveexec_b64 s[16:17], vcc
	v_add_f32_e32 v4, v4, v82
	v_ashrrev_i32_e32 v82, 1, v191
	v_add_u32_e32 v82, 0, v82
	v_add_u32_e32 v82, 0x20400, v82
	ds_write_b32 v82, v4
	s_or_b64 exec, exec, s[16:17]
	v_add_u32_e32 v234, s21, v192
	v_lshl_add_u32 v234, v234, 2, 0
	v_add_u32_e32 v234, 0x20000, v234
	ds_read_b128 v[236:239], v234
	v_lshl_add_u32 v235, v194, 2, 0
	v_add_u32_e32 v240, 0x20000, v235
	v_add_u32_e32 v235, 0x20100, v235
	ds_read_b32 v240, v240
	ds_read_b32 v241, v235
	v_lshl_add_u32 v4, v193, 2, 0
	v_add_u32_e32 v82, 0x20000, v4
	v_add_u32_e32 v4, 0x20100, v4
	ds_read_b32 v84, v82
	ds_read_b32 v4, v4
	v_add_u32_e32 v82, s21, v192
	v_cmp_le_i32_e64 s[16:17], v193, v82
	v_mov_b32_e32 v85, 0
	s_waitcnt lgkmcnt(0)
	v_sub_f32_e32 v93, v84, v4
	v_lshl_add_u32 v4, v82, 2, 0
	v_mov_b32_e32 v84, 0
	s_and_saveexec_b64 s[88:89], s[16:17]
	s_cbranch_execz .LBB0_385
	v_sub_f32_e32 v84, v236, v93
	v_mul_f32_e32 v84, 0x3fb8aa3b, v84
	v_exp_f32_e32 v84, v84
	s_nop 0
	v_mul_f32_e32 v84, v142, v84
	v_cvt_pk_bf16_f32 v84, v84, s0
; __device__ __forceinline__ bf16_t f2bf(float f) { const __bf16 r = (__bf16)f; bf16_t u; __builtin_memcpy(&u, &r, 2); return u; }
; __device__ __forceinline__ void mlstm_item(const P& p, const Ctx& c, int seg, int w, bool save) {
;     ...
;         for (int x = 0; x < 2; ++x) { const int ti = c.wv * 2 + x, tm = ti >> 2, tn = ti & 3; const int s = tn * 16 + l15; const float bs = bcum[s] - ipr[s];
; #pragma unroll
;             for (int jj = 0; jj < 4; ++jj) { const int t = tm * 16 + quad * 4 + jj; const float v = (s <= t) ? Sa[x][jj] * __expf(bcum[t] - bs) : 0.f; Sp[t * 72 + s] = f2bf(v); } }
.LBB0_385:
	s_or_b64 exec, exec, s[88:89]
	v_lshl_add_u32 v94, v193, 1, s0
	v_mul_lo_u32 v86, v82, s63
	v_add_u32_e32 v87, v94, v86
	ds_write_b16 v87, v84
	v_or_b32_e32 v87, 1, v82
	v_cmp_le_i32_e64 s[16:17], v193, v87
	v_lshl_add_u32 v84, v87, 2, 0
	s_and_saveexec_b64 s[88:89], s[16:17]
	s_cbranch_execz .LBB0_387
	v_sub_f32_e32 v85, v237, v93
	v_mul_f32_e32 v85, 0x3fb8aa3b, v85
	v_exp_f32_e32 v85, v85
	s_nop 0
	v_mul_f32_e32 v85, v143, v85
	v_cvt_pk_bf16_f32 v85, v85, s0
.LBB0_387:
	s_or_b64 exec, exec, s[88:89]
	v_add_u32_e32 v89, 0x90, v86
	v_add_u32_e32 v88, v94, v89
	v_or_b32_e32 v90, 2, v82
	ds_write_b16 v88, v85
	v_cmp_le_i32_e64 s[16:17], v193, v90
	v_mov_b32_e32 v95, 0
	v_lshl_add_u32 v85, v90, 2, 0
	v_mov_b32_e32 v88, 0
	s_and_saveexec_b64 s[88:89], s[16:17]
	s_cbranch_execz .LBB0_389
	v_sub_f32_e32 v88, v238, v93
	v_mul_f32_e32 v88, 0x3fb8aa3b, v88
	v_exp_f32_e32 v88, v88
	s_nop 0
	v_mul_f32_e32 v88, v144, v88
	v_cvt_pk_bf16_f32 v88, v88, s0
.LBB0_389:
	s_or_b64 exec, exec, s[88:89]
	v_add_u32_e32 v91, 0x90, v89
	v_add_u32_e32 v92, v94, v91
	ds_write_b16 v92, v88
	v_or_b32_e32 v92, 3, v82
	v_cmp_le_i32_e64 s[16:17], v193, v92
	v_lshl_add_u32 v88, v92, 2, 0
	s_and_saveexec_b64 s[88:89], s[16:17]
	s_cbranch_execz .LBB0_391
	v_sub_f32_e32 v93, v239, v93
	v_mul_f32_e32 v93, 0x3fb8aa3b, v93
	v_exp_f32_e32 v93, v93
	s_nop 0
	v_mul_f32_e32 v93, v145, v93
	v_cvt_pk_bf16_f32 v95, v93, s0
.LBB0_391:
	s_or_b64 exec, exec, s[88:89]
	v_add_u32_e32 v93, 0x90, v91
	v_add_u32_e32 v94, v94, v93
	ds_write_b16 v94, v95
	v_cmp_le_i32_e64 s[16:17], v194, v82
	v_mov_b32_e32 v96, 0
	v_mov_b32_e32 v97, 0
	s_waitcnt lgkmcnt(0)
	v_sub_f32_e32 v94, v240, v241
	s_and_saveexec_b64 s[88:89], s[16:17]
	s_cbranch_execz .LBB0_393
	v_sub_f32_e32 v95, v236, v94
	v_mul_f32_e32 v95, 0x3fb8aa3b, v95
	v_exp_f32_e32 v95, v95
	s_nop 0
	v_mul_f32_e32 v95, v138, v95
	v_cvt_pk_bf16_f32 v97, v95, s0
.LBB0_393:
	s_or_b64 exec, exec, s[88:89]
	v_lshlrev_b32_e32 v95, 1, v194
	v_add3_u32 v86, s0, v86, v95
	v_cmp_le_i32_e64 s[16:17], v194, v87
	ds_write_b16 v86, v97
	s_and_saveexec_b64 s[88:89], s[16:17]
	s_cbranch_execz .LBB0_395
	v_sub_f32_e32 v84, v237, v94
	v_mul_f32_e32 v84, 0x3fb8aa3b, v84
	v_exp_f32_e32 v84, v84
	s_nop 0
	v_mul_f32_e32 v84, v139, v84
	v_cvt_pk_bf16_f32 v96, v84, s0
.LBB0_395:
	s_or_b64 exec, exec, s[88:89]
	v_add3_u32 v84, s0, v89, v95
	ds_write_b16 v84, v96
	v_cmp_le_i32_e64 s[16:17], v194, v90
	v_mov_b32_e32 v84, 0
	v_mov_b32_e32 v86, 0
	s_and_saveexec_b64 s[88:89], s[16:17]
	s_cbranch_execz .LBB0_397
	v_sub_f32_e32 v85, v238, v94
	v_mul_f32_e32 v85, 0x3fb8aa3b, v85
	v_exp_f32_e32 v85, v85
	s_nop 0
	v_mul_f32_e32 v85, v140, v85
	v_cvt_pk_bf16_f32 v86, v85, s0
.LBB0_397:
	s_or_b64 exec, exec, s[88:89]
	v_add3_u32 v85, s0, v91, v95
	v_cmp_le_i32_e64 s[16:17], v194, v92
	ds_write_b16 v85, v86
	s_and_saveexec_b64 s[88:89], s[16:17]
	s_cbranch_execz .LBB0_399
	v_sub_f32_e32 v84, v239, v94
	v_mul_f32_e32 v84, 0x3fb8aa3b, v84
	v_exp_f32_e32 v84, v84
	s_nop 0
	v_mul_f32_e32 v84, v141, v84
	v_cvt_pk_bf16_f32 v84, v84, s0
